# v7 plus one static priority raise for the output waves of the role-split mLSTM output unit
# speedup vs baseline: 1.0082x; 1.0082x over previous
; __device__ __forceinline__ void ml_out_unit(LAS unsigned char* lds, const MixBufs& B, int b, int h, int seg, int tid) {
;     ...
;     if (outw) {
;         { int cg = cg0, ts = ts0; asm volatile("" : "+v"(cg), "+v"(ts)); MLO_PREFETCH(8 * seg); }
.LBB0_666:
	s_setprio 1
	v_mov_b32_e32 v2, v185
	v_mov_b32_e32 v6, v184
	s_lshl_b64 s[4:5], s[6:7], 11
	s_lshl_b32 s2, s24, 9
	v_readlane_b32 s36, v241, 18
	s_or_b32 s20, s4, s2
	v_lshlrev_b32_e32 v4, 2, v2
	v_readlane_b32 s50, v241, 32
	s_mov_b32 s21, s5
	v_ashrrev_i32_e32 v5, 31, v4
	v_readlane_b32 s51, v241, 33
	s_add_u32 s18, s50, s10
	v_lshlrev_b32_e32 v6, 2, v6
	v_lshl_add_u64 v[4:5], s[20:21], 0, v[4:5]
	s_addc_u32 s19, s51, 0
	v_ashrrev_i32_e32 v7, 31, v6
	v_lshl_add_u64 v[6:7], v[6:7], 1, s[18:19]
	v_lshlrev_b64 v[4:5], 10, v[4:5]
	v_lshl_add_u64 v[4:5], v[6:7], 0, v[4:5]
	v_ashrrev_i32_e32 v169, 31, v168
	global_load_dwordx2 v[52:53], v[4:5], off
	global_load_dwordx2 v[54:55], v[4:5], off offset:1024
	global_load_dwordx2 v[56:57], v[4:5], off offset:2048
	global_load_dwordx2 v[58:59], v[4:5], off offset:3072
	v_lshl_add_u64 v[4:5], s[20:21], 0, v[168:169]
	v_lshlrev_b64 v[4:5], 10, v[4:5]
	s_mov_b32 s2, s10
	s_mov_b32 s3, s9
	v_lshl_add_u64 v[4:5], s[0:1], 0, v[4:5]
	v_lshl_add_u64 v[4:5], v[4:5], 0, s[2:3]
	v_lshlrev_b32_e32 v2, 4, v189
	v_lshl_add_u64 v[4:5], v[4:5], 0, v[2:3]
	v_add_co_u32_e32 v8, vcc, 0x8000, v4
	v_cmp_gt_i32_e64 s[2:3], 64, v166
	s_nop 0
	v_addc_co_u32_e32 v9, vcc, 0, v5, vcc
	global_load_dwordx4 v[4:7], v[4:5], off nt
	s_nop 0
	global_load_dwordx4 v[8:11], v[8:9], off nt
	v_cmp_lt_i32_e32 vcc, 63, v166
	v_readlane_b32 s37, v241, 19
	v_readlane_b32 s38, v241, 20
	v_readlane_b32 s39, v241, 21
	v_readlane_b32 s40, v241, 22
	v_readlane_b32 s41, v241, 23
	v_readlane_b32 s42, v241, 24
	v_readlane_b32 s43, v241, 25
	v_readlane_b32 s44, v241, 26
	v_readlane_b32 s45, v241, 27
	v_readlane_b32 s46, v241, 28
	v_readlane_b32 s47, v241, 29
	v_readlane_b32 s48, v241, 30
	v_readlane_b32 s49, v241, 31
	s_and_saveexec_b64 s[22:23], vcc
	s_xor_b64 s[22:23], exec, s[22:23]
	v_mov_b32_e32 v167, v3
	s_or_saveexec_b64 s[22:23], s[22:23]
	v_mov_b32_e32 v153, 0
	v_mov_b32_e32 v152, 0
	v_mov_b32_e32 v162, 0
	s_xor_b64 exec, exec, s[22:23]
	s_cbranch_execz .LBB0_670
	v_ashrrev_i32_e32 v167, 31, v166
	v_lshl_add_u64 v[12:13], s[20:21], 0, v[166:167]
	v_lshlrev_b64 v[12:13], 4, v[12:13]
	v_readlane_b32 s20, v241, 59
	v_lshl_or_b32 v12, s8, 2, v12
	v_readlane_b32 s21, v241, 60
	s_nop 1
	v_lshl_add_u64 v[14:15], s[20:21], 0, v[12:13]
	v_readlane_b32 s20, v241, 61
	v_readlane_b32 s21, v241, 62
	global_load_dword v152, v[14:15], off
	s_nop 0
	v_lshl_add_u64 v[14:15], s[20:21], 0, v[12:13]
	v_readlane_b32 s20, v241, 63
	v_readlane_b32 s21, v240, 0
	global_load_dword v153, v[14:15], off
	s_nop 0
	v_lshl_add_u64 v[12:13], s[20:21], 0, v[12:13]
	global_load_dword v162, v[12:13], off

; __device__ __forceinline__ void ml_out_unit(LAS unsigned char* lds, const MixBufs& B, int b, int h, int seg, int tid) {
;     ...
;             __syncthreads();
;         }
;     } else {
.LBB0_678:
	s_setprio 0
	s_branch .LBB0_868
